# v9lreg
# baseline (speedup 1.0000x reference)
; __device__ __forceinline__ int otid() { int t = threadIdx.x; asm volatile("" : "+v"(t)); return t; }
; __device__ __forceinline__ unsigned lds_addr(LAS unsigned char* p) { return (unsigned)(size_t)p; }
; __device__ __forceinline__ int v_rd_base(int lane) { return ((lane & 3) << 3) | (((lane >> 2) & 3) << 6) | (((lane >> 4) & 1) << 5) | (((lane >> 5) & 1) << 8); }
; __device__ __forceinline__ void attn_block(const Params& p, LAS unsigned char* lds, int h, int qb) {
;     const int tid = otid(), wid = __builtin_amdgcn_readfirstlane(tid >> 6), lane = tid & 63, r32 = lane & 31, hi = lane >> 5;
;     const bf16_t* qbuf = (const bf16_t*)(p.ws + O_Q); const bf16_t* Kh = (const bf16_t*)(p.ws + O_K) + h * 192; const bf16_t* Vh = (const bf16_t*)(p.ws + O_V) + h * 128;
;     bf16_t* proj = (bf16_t*)(p.ws + O_PROJ);
;     const int qrow = qb * 256 + wid * 32 + r32;
;     bf16x8 qr[12];
;     { const bf16_t* qp = qbuf + (size_t)qrow * QW + h * 192 + hi * 8;
; #pragma unroll
;       for (int d0 = 0; d0 < 12; ++d0) qr[d0] = *(const bf16x8*)(qp + d0 * 16); }
;     const int ntiles = qb * 4 + 4, my_last = qb * 4 + (wid >> 1);
;     int ksrc[3], vsrc[2];
; #pragma unroll
;     for (int i = 0; i < 3; ++i) { const int j = i * 512 + tid, row = j / 24, cp = j % 24, c = (cp & ~7) | ((cp & 7) ^ ((row >> 1) & 7)); ksrc[i] = (row * KW + c * 8) * 2; }
; #pragma unroll
;     for (int i = 0; i < 2; ++i) { const int off = (i * 512 + tid) * 16, sub = off >> 9, rem = (off & 511) >> 1, kk = (sub >> 2) * 8 + (rem >> 5), c = (sub & 3) * 32 + (rem & 31);
;         const int k = (kk & ~0xC) | ((kk & 4) << 1) | ((kk & 8) >> 1); vsrc[i] = (k * VW + c) * 2; }
;     const int vb0 = (int)lds_addr(lds) + v_rd_base(lane);
;     const unsigned ldsw = (unsigned)wid * 1024u;
;     ...
;     float m_reg = -1e30f, l_reg = 0.f; f32x16 o[4];
; #pragma unroll
;     for (int j = 0; j < 4; ++j) o[j] = (f32x16){};
;     f32x16 pA0, pA1, pB0, pB1; float mnA, mnB, alA = 1.f, alB = 1.f; bf16x8 pa0, pa1, pa2, pa3;
;     ...
;     ADMA(0, 0, 0); __syncthreads();
;     ADMA(1, 1, 1);
;     qkt(0, pA0, pA1, lds, r32, hi, qr); partialSM(pA0, pA1, m_reg, mnA, alA);
.LBB0_324:
	v_mov_b32_e32 v8, v199
	s_and_b64 s[0:1], s[96:97], exec
	s_cselect_b32 s34, s16, s53
	v_readfirstlane_b32 s35, v8
	s_ashr_i32 s17, s35, 6
	s_lshl_b32 s0, s34, 8
	s_lshl_b32 s1, s17, 5
	v_and_b32_e32 v47, 31, v8
	s_add_i32 s1, s1, s0
	v_bfe_u32 v193, v8, 5, 1
	v_or_b32_e32 v180, s1, v47
	v_mov_b64_e32 v[2:3], s[44:45]
	v_mad_i64_i32 v[2:3], s[0:1], v180, s60, v[2:3]
	v_lshlrev_b32_e32 v0, 4, v193
	v_lshl_add_u64 v[2:3], v[2:3], 0, v[0:1]
	global_load_dwordx4 v[128:131], v[2:3], off
	global_load_dwordx4 v[132:135], v[2:3], off offset:32
	global_load_dwordx4 v[136:139], v[2:3], off offset:64
	global_load_dwordx4 v[140:143], v[2:3], off offset:96
	global_load_dwordx4 v[144:147], v[2:3], off offset:128
	global_load_dwordx4 v[148:151], v[2:3], off offset:160
	global_load_dwordx4 v[152:155], v[2:3], off offset:192
	global_load_dwordx4 v[156:159], v[2:3], off offset:224
	global_load_dwordx4 v[160:163], v[2:3], off offset:256
	global_load_dwordx4 v[164:167], v[2:3], off offset:288
	global_load_dwordx4 v[168:171], v[2:3], off offset:320
	global_load_dwordx4 v[172:175], v[2:3], off offset:352
	s_mov_b32 s0, 0x2aaaaaab
	v_mul_hi_i32 v0, v8, s0
	v_lshrrev_b32_e32 v2, 31, v0
	v_ashrrev_i32_e32 v0, 2, v0
	v_add_u32_e32 v0, v0, v2
	v_mul_lo_u32 v2, v0, 24
	v_sub_u32_e32 v2, v8, v2
	v_lshrrev_b32_e32 v3, 1, v0
	v_bitop3_b32 v2, v3, v2, 7 bitop3:0x6c
	v_mul_lo_u32 v0, v0, s60
	v_lshl_add_u32 v34, v2, 4, v0
	v_add_u32_e32 v0, 0x200, v8
	v_mul_hi_i32 v2, v0, s0
	v_lshrrev_b32_e32 v3, 31, v2
	v_ashrrev_i32_e32 v2, 2, v2
	v_add_u32_e32 v2, v2, v3
	v_mul_lo_u32 v3, v2, 24
	v_sub_u32_e32 v0, v0, v3
	v_lshrrev_b32_e32 v3, 1, v2
	v_bitop3_b32 v0, v3, v0, 7 bitop3:0x6c
	v_mul_lo_u32 v2, v2, s60
	v_lshl_add_u32 v36, v0, 4, v2
	v_add_u32_e32 v0, 0x400, v8
	v_mul_hi_i32 v2, v0, s0
	v_lshrrev_b32_e32 v3, 31, v2
	v_ashrrev_i32_e32 v2, 2, v2
	v_add_u32_e32 v2, v2, v3
	v_mul_lo_u32 v3, v2, 24
	v_sub_u32_e32 v0, v0, v3
	v_lshrrev_b32_e32 v3, 1, v2
	v_bitop3_b32 v0, v3, v0, 7 bitop3:0x6c
	v_lshlrev_b32_e32 v3, 4, v8
	v_mul_lo_u32 v2, v2, s60
	v_add_u32_e32 v10, 0x2000, v3
	v_lshl_add_u32 v38, v0, 4, v2
	v_lshrrev_b32_e32 v9, 1, v8
	v_bfe_i32 v2, v8, 4, 24
	v_ashrrev_i32_e32 v10, 8, v10
	v_and_b32_e32 v5, 63, v8
	v_bfe_u32 v0, v8, 2, 2
	v_and_b32_e32 v40, 8, v9
	v_lshlrev_b32_e32 v6, 1, v8
	v_and_b32_e32 v44, 0x1ffff0, v2
	v_lshrrev_b32_e32 v2, 1, v2
	v_and_b32_e32 v43, 0x1ffff0, v10
	v_lshrrev_b32_e32 v10, 1, v10
	v_or_b32_e32 v4, v40, v0
	v_and_b32_e32 v41, 0xc0, v6
	v_and_b32_e32 v42, 48, v3
	v_and_b32_e32 v46, 4, v2
	v_and_b32_e32 v45, 4, v10
	v_lshlrev_b32_e32 v5, 3, v5
	v_and_b32_e32 v3, 0xc0, v3
	s_lshl_b32 s0, s17, 10
	s_add_i32 s80, 0, 0x10000
	v_or_b32_e32 v7, v42, v41
	v_or3_b32 v2, v44, v46, v4
	v_or3_b32 v4, v43, v45, v4
	v_and_or_b32 v3, v5, 24, v3
	v_and_b32_e32 v6, 32, v6
	v_and_b32_e32 v5, 0x100, v5
	s_add_i32 s1, s80, s0
	v_ashrrev_i32_e32 v35, 31, v34
	v_lshl_or_b32 v2, v2, 11, v7
	v_lshl_or_b32 v4, v4, 11, v7
	v_or3_b32 v218, v3, v6, v5
	v_lshl_add_u64 v[6:7], s[42:43], 0, v[34:35]
	s_mov_b32 m0, s1
	v_ashrrev_i32_e32 v37, 31, v36
	global_load_lds_dwordx4 v[6:7], off
	v_lshl_add_u64 v[6:7], s[42:43], 0, v[36:37]
	s_add_i32 m0, s1, 0x2000
	v_ashrrev_i32_e32 v39, 31, v38
	global_load_lds_dwordx4 v[6:7], off
	v_lshl_add_u64 v[6:7], s[42:43], 0, v[38:39]
	s_add_i32 m0, s1, 0x4000
	s_add_i32 s17, s0, 0
	v_ashrrev_i32_e32 v3, 31, v2
	global_load_lds_dwordx4 v[6:7], off
	v_lshl_add_u64 v[6:7], s[12:13], 0, v[2:3]
	s_mov_b32 m0, s17
	v_ashrrev_i32_e32 v5, 31, v4
	global_load_lds_dwordx4 v[6:7], off
	v_lshl_add_u64 v[6:7], s[12:13], 0, v[4:5]
	s_add_i32 m0, s17, 0x2000
	s_add_i32 s49, s17, 0x16000
	global_load_lds_dwordx4 v[6:7], off
	v_lshl_add_u64 v[6:7], s[66:67], 0, v[34:35]
	s_mov_b32 m0, s49
	s_add_i32 s0, s17, 0x18000
	s_waitcnt vmcnt(0) lgkmcnt(0)
	s_barrier
	global_load_lds_dwordx4 v[6:7], off
	v_lshl_add_u64 v[6:7], s[66:67], 0, v[36:37]
	s_mov_b32 m0, s0
	s_add_i32 s1, s17, 0x1a000
	global_load_lds_dwordx4 v[6:7], off
	v_lshl_add_u64 v[6:7], s[66:67], 0, v[38:39]
	s_mov_b32 m0, s1
	v_lshl_add_u64 v[2:3], s[68:69], 0, v[2:3]
	global_load_lds_dwordx4 v[6:7], off
	s_add_i32 m0, s17, 0x4000
	s_nop 0
	global_load_lds_dwordx4 v[2:3], off
	v_lshl_add_u64 v[2:3], s[68:69], 0, v[4:5]
	s_add_i32 m0, s17, 0x6000
	v_bitop3_b32 v4, v193, v9, 7 bitop3:0x78
	global_load_lds_dwordx4 v[2:3], off
	v_bfe_u32 v3, v8, 1, 3
	v_lshlrev_b32_e32 v48, 4, v4
	v_bitop3_b32 v4, v193, v3, 2 bitop3:0x36
	v_mov_b32_e32 v2, s80
	s_movk_i32 s80, 0x180
	v_lshlrev_b32_e32 v49, 4, v4
	v_bitop3_b32 v4, v193, v3, 4 bitop3:0x36
	v_bitop3_b32 v3, v193, v3, 6 bitop3:0x36
	v_mad_u32_u24 v2, v47, s80, v2
	v_lshlrev_b32_e32 v50, 4, v4
	v_lshlrev_b32_e32 v51, 4, v3
	v_add_u32_e32 v181, v48, v2
	v_add_u32_e32 v219, v49, v2
	v_add_u32_e32 v220, v50, v2
	v_add_u32_e32 v221, v51, v2
	v_and_b32_e32 v52, 31, v199
	v_bfe_u32 v53, v199, 5, 1
	v_bfe_u32 v54, v52, 2, 1
	v_bfe_u32 v55, v52, 3, 1
	v_xor_b32_e32 v54, v54, v55
	v_mul_u32_u24_e32 v55, 12, v54
	v_xor_b32_e32 v56, v52, v55
	v_sub_u32_e32 v57, v56, v52
	v_mul_i32_i24_e32 v57, 0x180, v57
	v_bfe_u32 v54, v52, 1, 3
	v_bfe_u32 v55, v56, 1, 3
	v_or_b32_e32 v58, 0, v53
	v_xor_b32_e32 v59, v58, v55
	v_xor_b32_e32 v60, v58, v54
	v_sub_u32_e32 v59, v59, v60
	v_lshl_add_u32 v59, v59, 4, v57
	v_add_u32_e32 v181, v181, v59
	v_or_b32_e32 v58, 2, v53
	v_xor_b32_e32 v59, v58, v55
	v_xor_b32_e32 v60, v58, v54
	v_sub_u32_e32 v59, v59, v60
	v_lshl_add_u32 v59, v59, 4, v57
	v_add_u32_e32 v219, v219, v59
	v_or_b32_e32 v58, 4, v53
	v_xor_b32_e32 v59, v58, v55
	v_xor_b32_e32 v60, v58, v54
	v_sub_u32_e32 v59, v59, v60
	v_lshl_add_u32 v59, v59, 4, v57
	v_add_u32_e32 v220, v220, v59
	v_or_b32_e32 v58, 6, v53
	v_xor_b32_e32 v59, v58, v55
	v_xor_b32_e32 v60, v58, v54
	v_sub_u32_e32 v59, v59, v60
	v_lshl_add_u32 v59, v59, 4, v57
	v_add_u32_e32 v221, v221, v59
	ds_read_b128 v[2:5], v181 offset:0
	ds_read_b128 v[6:9], v181 offset:0x3000
	ds_read_b128 v[52:55], v219 offset:0
	ds_read_b128 v[56:59], v219 offset:0x3000
	s_cmp_lt_i32 s34, 0
	s_waitcnt lgkmcnt(0)
; #define LAS __attribute__((address_space(3)))
; __device__ __forceinline__ unsigned lds_addr(LAS unsigned char* p) { return (unsigned)(size_t)p; }
; #define KGRP(B_, g_) do { KRD(B_[0], kb[(2 * (g_)) & 3], ((2 * (g_)) >> 2) * 128); KRD(B_[1], kb[(2 * (g_)) & 3], ((2 * (g_)) >> 2) * 128 + 12288); \
;                           KRD(B_[2], kb[(2 * (g_) + 1) & 3], ((2 * (g_) + 1) >> 2) * 128); KRD(B_[3], kb[(2 * (g_) + 1) & 3], ((2 * (g_) + 1) >> 2) * 128 + 12288); } while (0)
; #define KWAIT(B_, n_) asm volatile("s_waitcnt lgkmcnt(" #n_ ")" : "+v"(B_[0]), "+v"(B_[1]), "+v"(B_[2]), "+v"(B_[3]) :: "memory")
; #define KWAIT(B_, n_) asm volatile("s_waitcnt lgkmcnt(" #n_ ")" : "+v"(B_[0]), "+v"(B_[1]) :: "memory")
; __device__ __forceinline__ void partialSM(f32x16& p0, f32x16& p1, float& m_reg, float& mn, float& alpha) {
;     float pmax = p0[0];
; #pragma unroll
;     for (int r = 1; r < 16; ++r) pmax = fmaxf(pmax, p0[r]);
; #pragma unroll
;     for (int r = 0; r < 16; ++r) pmax = fmaxf(pmax, p1[r]);
;     { auto rr = __builtin_amdgcn_permlane32_swap(__float_as_uint(pmax), __float_as_uint(pmax), false, false);
;       pmax = fmaxf(__uint_as_float(rr[0]), __uint_as_float(rr[1])); }
;     constexpr float C2 = 1.4426950408889634f * SCALE;
;     if (__builtin_expect(__all((pmax - m_reg) * SCALE <= THR), 1)) { mn = m_reg; alpha = 1.f; }
;     else { mn = fmaxf(m_reg, pmax); alpha = __builtin_amdgcn_exp2f((m_reg - mn) * C2); m_reg = mn; }
;     const float mnL = -mn * C2;
; #pragma unroll
;     for (int r = 0; r < 16; ++r) p0[r] = fmaf(p0[r], C2, mnL);
; #pragma unroll
;     for (int r = 0; r < 16; ++r) p1[r] = fmaf(p1[r], C2, mnL);
; #pragma unroll
;     for (int r = 0; r < 16; ++r) p0[r] = __builtin_amdgcn_exp2f(p0[r]);
; }
; __device__ __forceinline__ void qkt(int kboff, f32x16& p0, f32x16& p1, LAS unsigned char* lds, int r32, int hi, const bf16x8* qr) {
;     p0 = (f32x16){}; p1 = (f32x16){};
;     unsigned kb[4];
; #pragma unroll
;     for (int dd = 0; dd < 4; ++dd) kb[dd] = lds_addr(lds) + K_OFF + kboff + r32 * 384 + (((2 * dd + hi) ^ ((r32 >> 1) & 7)) << 4);
;     ...
;     bf16x8 bA[4];
;     KGRP(bA, 0); KWAIT(bA, 0); KMMA(bA, 0);
;     KGRP(bA, 1); KWAIT(bA, 0); KMMA(bA, 1);
;     KGRP(bA, 2); KWAIT(bA, 0); KMMA(bA, 2);
;     KGRP(bA, 3); KWAIT(bA, 0); KMMA(bA, 3);
;     KGRP(bA, 4); KWAIT(bA, 0); KMMA(bA, 4);
;     KGRP(bA, 5); KWAIT(bA, 0); KMMA(bA, 5);
	s_nop 0
	v_mfma_f32_32x32x16_bf16 v[18:33], v[2:5], v[128:131], 0
	v_mfma_f32_32x32x16_bf16 v[2:17], v[6:9], v[128:131], 0
	v_mfma_f32_32x32x16_bf16 v[18:33], v[52:55], v[132:135], v[18:33]
	ds_read_b128 v[52:55], v220 offset:0
	v_mfma_f32_32x32x16_bf16 v[2:17], v[56:59], v[132:135], v[2:17]
	ds_read_b128 v[56:59], v220 offset:0x3000
	ds_read_b128 v[60:63], v221 offset:0
	ds_read_b128 v[64:67], v221 offset:0x3000
	s_nop 0
	s_waitcnt lgkmcnt(0)
	s_nop 0
	v_mfma_f32_32x32x16_bf16 v[18:33], v[52:55], v[136:139], v[18:33]
	ds_read_b128 v[52:55], v181 offset:0x80
	v_mfma_f32_32x32x16_bf16 v[2:17], v[56:59], v[136:139], v[2:17]
	ds_read_b128 v[56:59], v181 offset:0x3080
	v_mfma_f32_32x32x16_bf16 v[18:33], v[60:63], v[140:143], v[18:33]
	ds_read_b128 v[60:63], v219 offset:0x80
	v_mfma_f32_32x32x16_bf16 v[2:17], v[64:67], v[140:143], v[2:17]
	ds_read_b128 v[64:67], v219 offset:0x3080
	s_nop 0
	s_waitcnt lgkmcnt(0)
	s_nop 0
	v_mfma_f32_32x32x16_bf16 v[18:33], v[52:55], v[144:147], v[18:33]
	ds_read_b128 v[52:55], v220 offset:0x80
	v_mfma_f32_32x32x16_bf16 v[2:17], v[56:59], v[144:147], v[2:17]
	ds_read_b128 v[56:59], v220 offset:0x3080
	v_mfma_f32_32x32x16_bf16 v[18:33], v[60:63], v[148:151], v[18:33]
	ds_read_b128 v[60:63], v221 offset:0x80
	v_mfma_f32_32x32x16_bf16 v[2:17], v[64:67], v[148:151], v[2:17]
	ds_read_b128 v[64:67], v221 offset:0x3080
	s_nop 0
	s_waitcnt lgkmcnt(0)
	s_nop 0
	v_mfma_f32_32x32x16_bf16 v[18:33], v[52:55], v[152:155], v[18:33]
	ds_read_b128 v[52:55], v181 offset:0x100
	v_mfma_f32_32x32x16_bf16 v[2:17], v[56:59], v[152:155], v[2:17]
	ds_read_b128 v[56:59], v181 offset:0x3100
	v_mfma_f32_32x32x16_bf16 v[18:33], v[60:63], v[156:159], v[18:33]
	ds_read_b128 v[60:63], v219 offset:0x100
	v_mfma_f32_32x32x16_bf16 v[2:17], v[64:67], v[156:159], v[2:17]
	ds_read_b128 v[64:67], v219 offset:0x3100
	s_nop 0
	s_waitcnt lgkmcnt(0)
	s_nop 0
	v_mfma_f32_32x32x16_bf16 v[18:33], v[52:55], v[160:163], v[18:33]
	ds_read_b128 v[52:55], v220 offset:0x100
	v_mfma_f32_32x32x16_bf16 v[2:17], v[56:59], v[160:163], v[2:17]
	ds_read_b128 v[56:59], v220 offset:0x3100
	v_mfma_f32_32x32x16_bf16 v[18:33], v[60:63], v[164:167], v[18:33]
	ds_read_b128 v[60:63], v221 offset:0x100
	v_mfma_f32_32x32x16_bf16 v[2:17], v[64:67], v[164:167], v[2:17]
	ds_read_b128 v[64:67], v221 offset:0x3100
	s_nop 0
	s_waitcnt lgkmcnt(0)
	s_waitcnt vmcnt(0) lgkmcnt(0)
	s_barrier
	v_mfma_f32_32x32x16_bf16 v[18:33], v[52:55], v[168:171], v[18:33]
	v_mfma_f32_32x32x16_bf16 v[18:33], v[60:63], v[172:175], v[18:33]
	v_mfma_f32_32x32x16_bf16 v[2:17], v[56:59], v[168:171], v[2:17]
	s_nop 10
	v_max_f32_e32 v52, v19, v19
	v_max_f32_e32 v53, v18, v18
	v_max_f32_e32 v52, v53, v52
	v_max3_f32 v52, v52, v20, v21
	v_max3_f32 v52, v52, v22, v23
	v_max3_f32 v52, v52, v24, v25
	v_max3_f32 v52, v52, v26, v27
	v_mfma_f32_32x32x16_bf16 v[2:17], v[64:67], v[172:175], v[2:17]
	v_max3_f32 v52, v52, v28, v29
	v_max3_f32 v52, v52, v30, v31
	v_max3_f32 v52, v52, v32, v33
	s_nop 8
	v_max3_f32 v52, v52, v2, v3
	v_max3_f32 v52, v52, v4, v5
	v_max3_f32 v52, v52, v6, v7
	v_max3_f32 v52, v52, v8, v9
	v_max3_f32 v52, v52, v10, v11
	v_max3_f32 v52, v52, v12, v13
	v_max3_f32 v52, v52, v14, v15
	v_max3_f32 v52, v52, v16, v17
	v_mov_b32_e32 v53, v52
	s_nop 1
	v_permlane32_swap_b32_e32 v52, v53
	v_max_f32_e32 v53, v53, v53
	v_max_f32_e32 v52, v52, v52
	v_max_f32_e32 v52, v52, v53
	v_add_f32_e32 v53, 0x7149f2ca, v52
	v_mul_f32_e32 v53, 0x3d93cd3a, v53
	v_cmp_ge_f32_e32 vcc, s63, v53
	s_cbranch_scc1 .LBB0_339
	s_lshl_b32 s34, s34, 2
	s_ashr_i32 s84, s35, 7
	s_add_i32 s80, s34, 4
	s_add_i32 s84, s84, s34
	s_cmp_eq_u64 vcc, exec
	v_max_f32_e32 v52, v52, v52
	v_max_f32_e32 v53, 0xf149f2ca, v52
	s_cselect_b64 vcc, -1, 0
	v_mov_b32_e32 v52, 0xf149f2ca
	v_cndmask_b32_e32 v244, v53, v52, vcc
	v_mul_f32_e32 v52, 0xbdd53b94, v244
	v_pk_fma_f32 v[214:215], v[2:3], s[52:53], v[52:53] op_sel_hi:[1,0,0]
	v_sub_f32_e32 v2, 0xf149f2ca, v53
	v_mul_f32_e32 v2, 0x3dd53b94, v2
	v_exp_f32_e32 v2, v2
	v_fmamk_f32 v18, v18, 0x3dd53b94, v52
	v_exp_f32_e32 v80, v18
	v_fmamk_f32 v18, v19, 0x3dd53b94, v52
	v_exp_f32_e32 v81, v18
	v_fmamk_f32 v18, v20, 0x3dd53b94, v52
	v_exp_f32_e32 v82, v18
	v_fmamk_f32 v18, v21, 0x3dd53b94, v52
	v_cndmask_b32_e64 v192, v2, 1.0, vcc
	v_add_u32_e32 v2, v44, v40
	v_exp_f32_e32 v83, v18
	v_fmamk_f32 v18, v22, 0x3dd53b94, v52
	v_add3_u32 v2, v2, v46, v0
	v_mul_u32_u24_e32 v47, 0x180, v47
	v_exp_f32_e32 v84, v18
	v_fmamk_f32 v18, v23, 0x3dd53b94, v52
	s_add_i32 s34, 0, 0x16000
	v_lshl_or_b32 v2, v2, 11, v41
	v_exp_f32_e32 v85, v18
	v_fmamk_f32 v18, v24, 0x3dd53b94, v52
	v_add_u32_e32 v3, s34, v47
	v_add_u32_e32 v2, v2, v42
	v_exp_f32_e32 v86, v18
	v_fmamk_f32 v18, v25, 0x3dd53b94, v52
	v_add_u32_e32 v226, v48, v3
	v_add_u32_e32 v227, v49, v3
	v_add_u32_e32 v228, v50, v3
	v_add_u32_e32 v229, v51, v3
	v_ashrrev_i32_e32 v3, 31, v2
	v_exp_f32_e32 v87, v18
	v_fmamk_f32 v18, v26, 0x3dd53b94, v52
	v_lshl_add_u64 v[182:183], s[50:51], 0, v[2:3]
	v_add_u32_e32 v2, v43, v40
	v_exp_f32_e32 v88, v18
	v_fmamk_f32 v18, v27, 0x3dd53b94, v52
	v_add3_u32 v0, v2, v45, v0
	v_exp_f32_e32 v89, v18
	v_fmamk_f32 v18, v28, 0x3dd53b94, v52
	v_fmamk_f32 v19, v29, 0x3dd53b94, v52
	v_fmamk_f32 v20, v30, 0x3dd53b94, v52
	v_fmamk_f32 v21, v31, 0x3dd53b94, v52
	v_fmamk_f32 v22, v32, 0x3dd53b94, v52
	v_fmamk_f32 v23, v33, 0x3dd53b94, v52
	v_lshl_or_b32 v0, v0, 11, v41
	v_exp_f32_e32 v90, v18
	v_exp_f32_e32 v91, v19
	v_add_u32_e32 v2, v0, v42
	v_exp_f32_e32 v92, v20
	v_exp_f32_e32 v93, v21
	v_exp_f32_e32 v94, v22
	v_exp_f32_e32 v95, v23
	v_pk_fma_f32 v[202:203], v[14:15], s[52:53], v[52:53] op_sel_hi:[1,0,0]
	v_ashrrev_i32_e32 v3, 31, v2
; __device__ __forceinline__ unsigned lds_addr(LAS unsigned char* p) { return (unsigned)(size_t)p; }
; __device__ __forceinline__ int v_rd_base(int lane) { return ((lane & 3) << 3) | (((lane >> 2) & 3) << 6) | (((lane >> 4) & 1) << 5) | (((lane >> 5) & 1) << 8); }
; __device__ __forceinline__ void attn_block(const Params& p, LAS unsigned char* lds, int h, int qb) {
;     ...
;     int ksrc[3], vsrc[2];
; #pragma unroll
;     for (int i = 0; i < 3; ++i) { const int j = i * 512 + tid, row = j / 24, cp = j % 24, c = (cp & ~7) | ((cp & 7) ^ ((row >> 1) & 7)); ksrc[i] = (row * KW + c * 8) * 2; }
; #pragma unroll
;     for (int i = 0; i < 2; ++i) { const int off = (i * 512 + tid) * 16, sub = off >> 9, rem = (off & 511) >> 1, kk = (sub >> 2) * 8 + (rem >> 5), c = (sub & 3) * 32 + (rem & 31);
;         const int k = (kk & ~0xC) | ((kk & 4) << 1) | ((kk & 8) >> 1); vsrc[i] = (k * VW + c) * 2; }
;     const int vb0 = (int)lds_addr(lds) + v_rd_base(lane);
;     const unsigned ldsw = (unsigned)wid * 1024u;
;     ...
;     float m_reg = -1e30f, l_reg = 0.f; f32x16 o[4];
; #pragma unroll
;     for (int j = 0; j < 4; ++j) o[j] = (f32x16){};
;     f32x16 pA0, pA1, pB0, pB1; float mnA, mnB, alA = 1.f, alB = 1.f; bf16x8 pa0, pa1, pa2, pa3;
	v_mov_b32_e32 v14, v1
	v_mov_b32_e32 v15, v1
	v_pk_fma_f32 v[200:201], v[16:17], s[52:53], v[52:53] op_sel_hi:[1,0,0]
	v_pk_fma_f32 v[204:205], v[12:13], s[52:53], v[52:53] op_sel_hi:[1,0,0]
	v_pk_fma_f32 v[206:207], v[10:11], s[52:53], v[52:53] op_sel_hi:[1,0,0]
	v_pk_fma_f32 v[208:209], v[8:9], s[52:53], v[52:53] op_sel_hi:[1,0,0]
	v_pk_fma_f32 v[210:211], v[6:7], s[52:53], v[52:53] op_sel_hi:[1,0,0]
	v_pk_fma_f32 v[212:213], v[4:5], s[52:53], v[52:53] op_sel_hi:[1,0,0]
	v_lshl_add_u64 v[184:185], s[50:51], 0, v[2:3]
	v_lshl_add_u64 v[186:187], s[40:41], 0, v[34:35]
	v_lshl_add_u64 v[188:189], s[40:41], 0, v[36:37]
	v_lshl_add_u64 v[190:191], s[40:41], 0, v[38:39]
	v_mov_b32_e32 v0, v1
	v_mov_b32_e32 v2, v1
	v_mov_b32_e32 v3, v1
	v_mov_b32_e32 v4, v1
	v_mov_b32_e32 v5, v1
	v_mov_b32_e32 v6, v1
	v_mov_b32_e32 v7, v1
	v_mov_b32_e32 v8, v1
	v_mov_b32_e32 v9, v1
	v_mov_b32_e32 v10, v1
	v_mov_b32_e32 v11, v1
	v_mov_b32_e32 v12, v1
	v_mov_b32_e32 v13, v1
	v_mov_b64_e32 v[30:31], v[14:15]
	v_mov_b64_e32 v[46:47], v[14:15]
	v_mov_b64_e32 v[62:63], v[14:15]
	v_mov_b64_e32 v[78:79], v[14:15]
	v_add_u32_e32 v225, 0, v218
	v_mov_b32_e32 v245, 0
	s_mov_b32 s86, 1
	s_mov_b32 s85, 0x10000
	v_mov_b64_e32 v[28:29], v[12:13]
	v_mov_b64_e32 v[26:27], v[10:11]
	v_mov_b64_e32 v[24:25], v[8:9]
	v_mov_b64_e32 v[22:23], v[6:7]
	v_mov_b64_e32 v[20:21], v[4:5]
	v_mov_b64_e32 v[18:19], v[2:3]
	v_mov_b64_e32 v[16:17], v[0:1]
	v_mov_b64_e32 v[44:45], v[12:13]
	v_mov_b64_e32 v[42:43], v[10:11]
	v_mov_b64_e32 v[40:41], v[8:9]
	v_mov_b64_e32 v[38:39], v[6:7]
	v_mov_b64_e32 v[36:37], v[4:5]
	v_mov_b64_e32 v[34:35], v[2:3]
	v_mov_b64_e32 v[32:33], v[0:1]
	v_mov_b64_e32 v[60:61], v[12:13]
	v_mov_b64_e32 v[58:59], v[10:11]
	v_mov_b64_e32 v[56:57], v[8:9]
	v_mov_b64_e32 v[54:55], v[6:7]
	v_mov_b64_e32 v[52:53], v[4:5]
	v_mov_b64_e32 v[50:51], v[2:3]
	v_mov_b64_e32 v[48:49], v[0:1]
	v_mov_b64_e32 v[76:77], v[12:13]
	v_mov_b64_e32 v[74:75], v[10:11]
	v_mov_b64_e32 v[72:73], v[8:9]
	v_mov_b64_e32 v[70:71], v[6:7]
	v_mov_b64_e32 v[68:69], v[4:5]
	v_mov_b64_e32 v[66:67], v[2:3]
	v_mov_b64_e32 v[64:65], v[0:1]
	s_mov_b64 s[54:55], 0x2ba60000
	s_mov_b64 s[56:57], 0x2ea40000
	v_mul_u32_u24_e32 v4, 0xaab, v199
	v_lshrrev_b32_e32 v4, 16, v4
	v_mul_u32_u24_e32 v5, 24, v4
	v_sub_u32_e32 v5, v199, v5
	v_bfe_u32 v6, v4, 1, 3
	v_and_b32_e32 v7, 7, v5
	v_xor_b32_e32 v7, v7, v6
	v_and_or_b32 v7, v5, 24, v7
	v_mul_u32_u24_e32 v4, 0xc00, v4
	v_lshl_add_u32 v8, v7, 4, v4
	v_lshl_add_u64 v[10:11], s[14:15], 0, v[186:187]
	v_lshl_add_u64 v[10:11], v[10:11], 0, s[54:55]
	v_sub_co_u32_e64 v10, s[98:99], v10, v8
	s_nop 1
	v_subbrev_co_u32_e64 v11, s[98:99], 0, v11, s[98:99]
	v_lshrrev_b32_e32 v4, 7, v199
	v_bfe_u32 v5, v199, 2, 3
	v_lshl_or_b32 v4, v4, 3, v5
	v_and_b32_e32 v5, 0xfffffff3, v4
	v_and_b32_e32 v6, 4, v4
	v_lshl_or_b32 v5, v6, 1, v5
	v_and_b32_e32 v6, 8, v4
	v_lshrrev_b32_e32 v6, 1, v6
	v_or_b32_e32 v5, v5, v6
	v_bfe_u32 v6, v199, 5, 2
	v_and_b32_e32 v7, 3, v199
	v_lshlrev_b32_e32 v6, 6, v6
	v_lshl_or_b32 v6, v7, 4, v6
	v_lshl_add_u32 v9, v5, 11, v6
	v_lshl_add_u64 v[12:13], s[14:15], 0, v[182:183]
	v_lshl_add_u64 v[12:13], v[12:13], 0, s[56:57]
	v_sub_co_u32_e64 v12, s[98:99], v12, v9
	s_nop 1
	v_subbrev_co_u32_e64 v13, s[98:99], 0, v13, s[98:99]
	s_nop 1
	v_readfirstlane_b32 s54, v10
	v_readfirstlane_b32 s55, v11
	v_readfirstlane_b32 s56, v12
	v_readfirstlane_b32 s57, v13
	v_mul_u32_u24_e32 v4, 0xaab, v199
	v_lshrrev_b32_e32 v4, 16, v4
	v_mul_u32_u24_e32 v5, 24, v4
	v_sub_u32_e32 v5, v199, v5
	v_bfe_u32 v6, v4, 1, 3
	v_and_b32_e32 v7, 7, v5
	v_xor_b32_e32 v7, v7, v6
	v_and_or_b32 v7, v5, 24, v7
	v_mul_u32_u24_e32 v4, 0xc00, v4
	v_lshl_add_u32 v186, v7, 4, v4
	v_add_u32_e32 v3, 256, v199
	v_mul_u32_u24_e32 v4, 0xaab, v3
	v_lshrrev_b32_e32 v4, 16, v4
	v_mul_u32_u24_e32 v5, 24, v4
	v_sub_u32_e32 v5, v3, v5
	v_bfe_u32 v6, v4, 1, 3
	v_and_b32_e32 v7, 7, v5
	v_xor_b32_e32 v7, v7, v6
	v_and_or_b32 v7, v5, 24, v7
	v_mul_u32_u24_e32 v4, 0xc00, v4
; __device__ __forceinline__ unsigned lds_addr(LAS unsigned char* p) { return (unsigned)(size_t)p; }
; __device__ __forceinline__ int v_rd_base(int lane) { return ((lane & 3) << 3) | (((lane >> 2) & 3) << 6) | (((lane >> 4) & 1) << 5) | (((lane >> 5) & 1) << 8); }
; __device__ __forceinline__ void qkt(int kboff, f32x16& p0, f32x16& p1, LAS unsigned char* lds, int r32, int hi, const bf16x8* qr) {
;     ...
;     for (int dd = 0; dd < 4; ++dd) kb[dd] = lds_addr(lds) + K_OFF + kboff + r32 * 384 + (((2 * dd + hi) ^ ((r32 >> 1) & 7)) << 4);
; __device__ __forceinline__ void attn_block(const Params& p, LAS unsigned char* lds, int h, int qb) {
;     ...
;     int ksrc[3], vsrc[2];
; #pragma unroll
;     for (int i = 0; i < 3; ++i) { const int j = i * 512 + tid, row = j / 24, cp = j % 24, c = (cp & ~7) | ((cp & 7) ^ ((row >> 1) & 7)); ksrc[i] = (row * KW + c * 8) * 2; }
; #pragma unroll
;     for (int i = 0; i < 2; ++i) { const int off = (i * 512 + tid) * 16, sub = off >> 9, rem = (off & 511) >> 1, kk = (sub >> 2) * 8 + (rem >> 5), c = (sub & 3) * 32 + (rem & 31);
;         const int k = (kk & ~0xC) | ((kk & 4) << 1) | ((kk & 8) >> 1); vsrc[i] = (k * VW + c) * 2; }
;     const int vb0 = (int)lds_addr(lds) + v_rd_base(lane);
;     const unsigned ldsw = (unsigned)wid * 1024u;
	v_lshl_add_u32 v187, v7, 4, v4
	v_add_u32_e32 v3, 512, v199
	v_mul_u32_u24_e32 v4, 0xaab, v3
	v_lshrrev_b32_e32 v4, 16, v4
	v_mul_u32_u24_e32 v5, 24, v4
	v_sub_u32_e32 v5, v3, v5
	v_bfe_u32 v6, v4, 1, 3
	v_and_b32_e32 v7, 7, v5
	v_xor_b32_e32 v7, v7, v6
	v_and_or_b32 v7, v5, 24, v7
	v_mul_u32_u24_e32 v4, 0xc00, v4
	v_lshl_add_u32 v188, v7, 4, v4
	v_add_u32_e32 v3, 768, v199
	v_mul_u32_u24_e32 v4, 0xaab, v3
	v_lshrrev_b32_e32 v4, 16, v4
	v_mul_u32_u24_e32 v5, 24, v4
	v_sub_u32_e32 v5, v3, v5
	v_bfe_u32 v6, v4, 1, 3
	v_and_b32_e32 v7, 7, v5
	v_xor_b32_e32 v7, v7, v6
	v_and_or_b32 v7, v5, 24, v7
	v_mul_u32_u24_e32 v4, 0xc00, v4
	v_lshl_add_u32 v189, v7, 4, v4
	v_add_u32_e32 v3, 1024, v199
	v_mul_u32_u24_e32 v4, 0xaab, v3
	v_lshrrev_b32_e32 v4, 16, v4
	v_mul_u32_u24_e32 v5, 24, v4
	v_sub_u32_e32 v5, v3, v5
	v_bfe_u32 v6, v4, 1, 3
	v_and_b32_e32 v7, 7, v5
	v_xor_b32_e32 v7, v7, v6
	v_and_or_b32 v7, v5, 24, v7
	v_mul_u32_u24_e32 v4, 0xc00, v4
	v_lshl_add_u32 v190, v7, 4, v4
	v_add_u32_e32 v3, 1280, v199
	v_mul_u32_u24_e32 v4, 0xaab, v3
	v_lshrrev_b32_e32 v4, 16, v4
	v_mul_u32_u24_e32 v5, 24, v4
	v_sub_u32_e32 v5, v3, v5
	v_bfe_u32 v6, v4, 1, 3
	v_and_b32_e32 v7, 7, v5
	v_xor_b32_e32 v7, v7, v6
	v_and_or_b32 v7, v5, 24, v7
	v_mul_u32_u24_e32 v4, 0xc00, v4
	v_lshl_add_u32 v191, v7, 4, v4
	v_lshrrev_b32_e32 v4, 7, v199
	v_bfe_u32 v5, v199, 2, 3
	v_lshl_or_b32 v4, v4, 3, v5
	v_and_b32_e32 v5, 0xfffffff3, v4
	v_and_b32_e32 v6, 4, v4
	v_lshl_or_b32 v5, v6, 1, v5
	v_and_b32_e32 v6, 8, v4
	v_lshrrev_b32_e32 v6, 1, v6
	v_or_b32_e32 v5, v5, v6
	v_bfe_u32 v6, v199, 5, 2
	v_and_b32_e32 v7, 3, v199
	v_lshlrev_b32_e32 v6, 6, v6
	v_lshl_or_b32 v6, v7, 4, v6
	v_lshl_add_u32 v182, v5, 11, v6
	v_add_u32_e32 v3, 256, v199
	v_lshrrev_b32_e32 v4, 7, v3
	v_bfe_u32 v5, v3, 2, 3
	v_lshl_or_b32 v4, v4, 3, v5
	v_and_b32_e32 v5, 0xfffffff3, v4
	v_and_b32_e32 v6, 4, v4
	v_lshl_or_b32 v5, v6, 1, v5
	v_and_b32_e32 v6, 8, v4
	v_lshrrev_b32_e32 v6, 1, v6
	v_or_b32_e32 v5, v5, v6
	v_bfe_u32 v6, v3, 5, 2
	v_and_b32_e32 v7, 3, v3
	v_lshlrev_b32_e32 v6, 6, v6
	v_lshl_or_b32 v6, v7, 4, v6
	v_lshl_add_u32 v183, v5, 11, v6
	v_add_u32_e32 v3, 512, v199
	v_lshrrev_b32_e32 v4, 7, v3
	v_bfe_u32 v5, v3, 2, 3
	v_lshl_or_b32 v4, v4, 3, v5
	v_and_b32_e32 v5, 0xfffffff3, v4
	v_and_b32_e32 v6, 4, v4
	v_lshl_or_b32 v5, v6, 1, v5
	v_and_b32_e32 v6, 8, v4
	v_lshrrev_b32_e32 v6, 1, v6
	v_or_b32_e32 v5, v5, v6
	v_bfe_u32 v6, v3, 5, 2
	v_and_b32_e32 v7, 3, v3
	v_lshlrev_b32_e32 v6, 6, v6
	v_lshl_or_b32 v6, v7, 4, v6
	v_lshl_add_u32 v184, v5, 11, v6
	v_add_u32_e32 v3, 768, v199
	v_lshrrev_b32_e32 v4, 7, v3
	v_bfe_u32 v5, v3, 2, 3
	v_lshl_or_b32 v4, v4, 3, v5
	v_and_b32_e32 v5, 0xfffffff3, v4
	v_and_b32_e32 v6, 4, v4
	v_lshl_or_b32 v5, v6, 1, v5
	v_and_b32_e32 v6, 8, v4
	v_lshrrev_b32_e32 v6, 1, v6
	v_or_b32_e32 v5, v5, v6
	v_bfe_u32 v6, v3, 5, 2
	v_and_b32_e32 v7, 3, v3
	v_lshlrev_b32_e32 v6, 6, v6
	v_lshl_or_b32 v6, v7, 4, v6
	v_lshl_add_u32 v185, v5, 11, v6
	s_nop 4
	v_and_b32_e32 v4, 31, v199
	v_bfe_u32 v5, v199, 5, 1
	v_bfe_u32 v6, v4, 2, 1
	v_bfe_u32 v7, v4, 3, 1
	v_xor_b32_e32 v6, v6, v7
	v_mul_u32_u24_e32 v7, 12, v6
	v_xor_b32_e32 v8, v4, v7
	v_sub_u32_e32 v9, v8, v4
	v_mul_i32_i24_e32 v9, 0x180, v9
	v_bfe_u32 v6, v4, 1, 3
	v_bfe_u32 v7, v8, 1, 3
	v_or_b32_e32 v10, 0, v5
	v_xor_b32_e32 v11, v10, v7
	v_xor_b32_e32 v12, v10, v6
	v_sub_u32_e32 v11, v11, v12
	v_lshl_add_u32 v11, v11, 4, v9
	v_add_u32_e32 v226, v226, v11
	v_or_b32_e32 v10, 2, v5
	v_xor_b32_e32 v11, v10, v7
	v_xor_b32_e32 v12, v10, v6
	v_sub_u32_e32 v11, v11, v12
	v_lshl_add_u32 v11, v11, 4, v9
	v_add_u32_e32 v227, v227, v11
	v_or_b32_e32 v10, 4, v5
	v_xor_b32_e32 v11, v10, v7
	v_xor_b32_e32 v12, v10, v6
	v_sub_u32_e32 v11, v11, v12
	v_lshl_add_u32 v11, v11, 4, v9
	v_add_u32_e32 v228, v228, v11
	v_or_b32_e32 v10, 6, v5
	v_xor_b32_e32 v11, v10, v7
	v_xor_b32_e32 v12, v10, v6
	v_sub_u32_e32 v11, v11, v12
	v_lshl_add_u32 v11, v11, 4, v9
	v_add_u32_e32 v229, v229, v11

; #define LAS __attribute__((address_space(3)))
; __device__ __forceinline__ unsigned lds_addr(LAS unsigned char* p) { return (unsigned)(size_t)p; }
; #define SBAR() __builtin_amdgcn_sched_barrier(0)
; template <int k> __device__ __forceinline__ void fin_snip(f32x16& p0, f32x16& p1, float alpha, float& l_reg, float& ps, bf16x8& pa0, bf16x8& pa1, bf16x8& pa2, bf16x8& pa3) {
;     if constexpr (k < 8) { p1[2 * k] = __builtin_amdgcn_exp2f(p1[2 * k]); p1[2 * k + 1] = __builtin_amdgcn_exp2f(p1[2 * k + 1]); }
;     else if constexpr (k < 16) { constexpr int j = 2 * (k - 8); const float a = (p0[j] + p0[j + 1]) + (p1[j] + p1[j + 1]); ps = (k == 8) ? a : ps + a; }
;     else if constexpr (k == 16) { auto rr = __builtin_amdgcn_permlane32_swap(__float_as_uint(ps), __float_as_uint(ps), false, false);
;         ps = __uint_as_float(rr[0]) + __uint_as_float(rr[1]); l_reg = l_reg * alpha + ps; }
;     else if constexpr (k == 17) { PK4(p0, 0, pa0); }
;     else if constexpr (k == 18) { PK4(p0, 8, pa1); }
;     else if constexpr (k == 19) { PK4(p1, 0, pa2); }
;     else if constexpr (k == 20) { PK4(p1, 8, pa3); }
; }
; __device__ __forceinline__ void stage_qk_fin(int kboff, f32x16& x0, f32x16& x1, LAS unsigned char* lds, int r32, int hi, const bf16x8* qr,
;                                              f32x16& y0, f32x16& y1, float alY, float& l_reg, bf16x8& pa0, bf16x8& pa1, bf16x8& pa2, bf16x8& pa3) {
;     x0 = (f32x16){}; x1 = (f32x16){};
;     unsigned kb[4];
; #pragma unroll
;     for (int dd = 0; dd < 4; ++dd) kb[dd] = lds_addr(lds) + K_OFF + kboff + r32 * 384 + (((2 * dd + hi) ^ ((r32 >> 1) & 7)) << 4);
;     ...
;     float ps = 0.f; bf16x8 bA[2], bB[2];
;     SBAR(); KGRP(bA, 0); KGRP(bB, 1); KWAIT(bA, 2); SBAR();
;     KMS(bA, 0); KGRP(bA, 2); KWAIT(bB, 2); SBAR();
;     KMS(bB, 1); KGRP(bB, 3); KWAIT(bA, 2); SBAR();
;     KMS(bA, 2); KGRP(bA, 4); KWAIT(bB, 2); SBAR();
;     KMS(bB, 3); KGRP(bB, 5); KWAIT(bA, 2); SBAR();
;     KMS(bA, 4); KGRP(bA, 6); KWAIT(bB, 2); SBAR();
;     KMS(bB, 5); KGRP(bB, 7); KWAIT(bA, 2); SBAR();
;     KMS(bA, 6); KGRP(bA, 8); KWAIT(bB, 2); SBAR();
;     KMS(bB, 7); KGRP(bB, 9); KWAIT(bA, 2); SBAR();
;     KMS(bA, 8); KGRP(bA, 10); KWAIT(bB, 2); SBAR();
;     KMS(bB, 9); KGRP(bB, 11); KWAIT(bA, 2); SBAR();
;     KMS(bA, 10); KWAIT(bB, 0); SBAR();
;     KMS(bB, 11);
.LBB0_328:
	s_cmp_gt_i32 s86, s84
	s_cselect_b64 vcc, -1, 0
	v_cndmask_b32_e32 v216, 0, v223, vcc
	ds_read_b128 v[2:5], v226 offset:0
	ds_read_b128 v[6:9], v226 offset:0x3000
	ds_read_b128 v[10:13], v227 offset:0
	ds_read_b128 v[176:179], v227 offset:0x3000
	s_nop 0
	s_waitcnt lgkmcnt(2)
	s_nop 0
	v_mfma_f32_32x32x16_bf16 v[96:111], v[2:5], v[128:131], 0
	v_exp_f32_e32 v214, v214
	v_exp_f32_e32 v215, v215
	v_mfma_f32_32x32x16_bf16 v[112:127], v[6:9], v[128:131], 0
	v_exp_f32_e32 v212, v212
	v_exp_f32_e32 v213, v213
	ds_read_b128 v[2:5], v228 offset:0
	ds_read_b128 v[6:9], v228 offset:0x3000
	s_waitcnt lgkmcnt(2)
	s_nop 0
	v_mfma_f32_32x32x16_bf16 v[96:111], v[10:13], v[132:135], v[96:111]
	v_exp_f32_e32 v210, v210
	v_exp_f32_e32 v211, v211
	v_mfma_f32_32x32x16_bf16 v[112:127], v[176:179], v[132:135], v[112:127]
	v_exp_f32_e32 v208, v208
	v_exp_f32_e32 v209, v209
	ds_read_b128 v[10:13], v229 offset:0
	ds_read_b128 v[176:179], v229 offset:0x3000
	s_waitcnt lgkmcnt(2)
	s_nop 0
	v_mfma_f32_32x32x16_bf16 v[96:111], v[2:5], v[136:139], v[96:111]
	v_exp_f32_e32 v206, v206
	v_exp_f32_e32 v207, v207
	v_mfma_f32_32x32x16_bf16 v[112:127], v[6:9], v[136:139], v[112:127]
	v_exp_f32_e32 v204, v204
	v_exp_f32_e32 v205, v205
	ds_read_b128 v[2:5], v226 offset:0x80
	ds_read_b128 v[6:9], v226 offset:0x3080
	s_waitcnt lgkmcnt(2)
	s_nop 0
	v_mfma_f32_32x32x16_bf16 v[96:111], v[10:13], v[140:143], v[96:111]
	v_exp_f32_e32 v202, v202
	v_exp_f32_e32 v203, v203
	v_mfma_f32_32x32x16_bf16 v[112:127], v[176:179], v[140:143], v[112:127]
	v_exp_f32_e32 v200, v200
	v_exp_f32_e32 v201, v201
	ds_read_b128 v[10:13], v227 offset:0x80
	ds_read_b128 v[176:179], v227 offset:0x3080
	s_waitcnt lgkmcnt(2)
	s_nop 0
	v_mfma_f32_32x32x16_bf16 v[96:111], v[2:5], v[144:147], v[96:111]
	v_add_f32_e32 v0, v80, v81
	v_add_f32_e32 v2, v214, v215
	v_add_f32_e32 v0, v0, v2
	v_mfma_f32_32x32x16_bf16 v[112:127], v[6:9], v[144:147], v[112:127]
	v_add_f32_e32 v2, v82, v83
	v_add_f32_e32 v3, v212, v213
	v_add_f32_e32 v2, v2, v3
	v_add_f32_e32 v0, v0, v2
	ds_read_b128 v[2:5], v228 offset:0x80
	ds_read_b128 v[6:9], v228 offset:0x3080
	s_waitcnt lgkmcnt(2)
	s_nop 0
	v_mfma_f32_32x32x16_bf16 v[96:111], v[10:13], v[148:151], v[96:111]
	v_add_f32_e32 v10, v84, v85
	v_add_f32_e32 v11, v210, v211
	v_add_f32_e32 v10, v10, v11
	v_add_f32_e32 v0, v10, v0
	v_mfma_f32_32x32x16_bf16 v[112:127], v[176:179], v[148:151], v[112:127]
	v_add_f32_e32 v10, v86, v87
	v_add_f32_e32 v11, v208, v209
	v_add_f32_e32 v10, v10, v11
	v_add_f32_e32 v0, v10, v0
	ds_read_b128 v[10:13], v229 offset:0x80
	ds_read_b128 v[176:179], v229 offset:0x3080
	s_waitcnt lgkmcnt(2)
	s_nop 0
	v_mfma_f32_32x32x16_bf16 v[96:111], v[2:5], v[152:155], v[96:111]
	v_add_f32_e32 v2, v88, v89
	v_add_f32_e32 v3, v206, v207
	v_add_f32_e32 v2, v2, v3
	v_add_f32_e32 v0, v2, v0
	v_mfma_f32_32x32x16_bf16 v[112:127], v[6:9], v[152:155], v[112:127]
	v_add_f32_e32 v2, v90, v91
	v_add_f32_e32 v3, v204, v205
	v_add_f32_e32 v2, v2, v3
	v_add_f32_e32 v0, v2, v0
	ds_read_b128 v[2:5], v226 offset:0x100
	ds_read_b128 v[6:9], v226 offset:0x3100
	s_waitcnt lgkmcnt(2)
	s_nop 0
	v_mfma_f32_32x32x16_bf16 v[96:111], v[10:13], v[156:159], v[96:111]
	v_add_f32_e32 v10, v92, v93
	v_add_f32_e32 v11, v202, v203
	v_add_f32_e32 v10, v10, v11
	v_add_f32_e32 v0, v10, v0
	v_mfma_f32_32x32x16_bf16 v[112:127], v[176:179], v[156:159], v[112:127]
	v_add_f32_e32 v10, v94, v95
	v_add_f32_e32 v11, v200, v201
	v_add_f32_e32 v10, v10, v11
	v_add_f32_e32 v14, v10, v0
	ds_read_b128 v[10:13], v227 offset:0x100
	ds_read_b128 v[176:179], v227 offset:0x3100
	s_waitcnt lgkmcnt(2)
	s_nop 0
	v_mfma_f32_32x32x16_bf16 v[96:111], v[2:5], v[160:163], v[96:111]
	v_mov_b32_e32 v15, v14
	s_nop 1
	v_permlane32_swap_b32_e32 v14, v15
	v_mfma_f32_32x32x16_bf16 v[112:127], v[6:9], v[160:163], v[112:127]
	v_cvt_pk_bf16_f32 v2, v80, v81
	v_cvt_pk_bf16_f32 v3, v82, v83
	v_cvt_pk_bf16_f32 v4, v84, v85
	v_cvt_pk_bf16_f32 v5, v86, v87
	ds_read_b128 v[194:197], v228 offset:0x100
	ds_read_b128 v[232:235], v228 offset:0x3100
	s_waitcnt lgkmcnt(2)
	s_nop 0
	v_mfma_f32_32x32x16_bf16 v[96:111], v[10:13], v[164:167], v[96:111]
	v_cvt_pk_bf16_f32 v6, v88, v89
	v_cvt_pk_bf16_f32 v7, v90, v91
	v_cvt_pk_bf16_f32 v8, v92, v93
	v_cvt_pk_bf16_f32 v9, v94, v95
	v_mfma_f32_32x32x16_bf16 v[112:127], v[176:179], v[164:167], v[112:127]
	v_cvt_pk_bf16_f32 v10, v214, v215
	v_cvt_pk_bf16_f32 v11, v212, v213
	v_cvt_pk_bf16_f32 v12, v210, v211
	v_cvt_pk_bf16_f32 v13, v208, v209
	ds_read_b128 v[236:239], v229 offset:0x100
	ds_read_b128 v[240:243], v229 offset:0x3100
	s_waitcnt lgkmcnt(2)
	s_nop 0
	v_mfma_f32_32x32x16_bf16 v[96:111], v[194:197], v[168:171], v[96:111]
	v_cvt_pk_bf16_f32 v176, v206, v207
	v_cvt_pk_bf16_f32 v177, v204, v205
	v_cvt_pk_bf16_f32 v178, v202, v203
	v_cvt_pk_bf16_f32 v179, v200, v201
	v_mfma_f32_32x32x16_bf16 v[112:127], v[232:235], v[168:171], v[112:127]
	v_add_f32_e32 v247, v14, v15
	v_fma_f32 v245, v192, v245, v247
	s_waitcnt lgkmcnt(0)
	s_nop 0
	v_mfma_f32_32x32x16_bf16 v[96:111], v[236:239], v[172:175], v[96:111]
	v_mfma_f32_32x32x16_bf16 v[112:127], v[240:243], v[172:175], v[112:127]
	s_cmp_eq_u32 s100, 0
	s_cbranch_scc1 .Lmy_mid_a
	s_waitcnt vmcnt(0)
	s_barrier

; #define LAS __attribute__((address_space(3)))
; __device__ __forceinline__ unsigned lds_addr(LAS unsigned char* p) { return (unsigned)(size_t)p; }
; #define SBAR() __builtin_amdgcn_sched_barrier(0)
; template <int k> __device__ __forceinline__ void fin_snip(f32x16& p0, f32x16& p1, float alpha, float& l_reg, float& ps, bf16x8& pa0, bf16x8& pa1, bf16x8& pa2, bf16x8& pa3) {
;     if constexpr (k < 8) { p1[2 * k] = __builtin_amdgcn_exp2f(p1[2 * k]); p1[2 * k + 1] = __builtin_amdgcn_exp2f(p1[2 * k + 1]); }
;     else if constexpr (k < 16) { constexpr int j = 2 * (k - 8); const float a = (p0[j] + p0[j + 1]) + (p1[j] + p1[j + 1]); ps = (k == 8) ? a : ps + a; }
;     else if constexpr (k == 16) { auto rr = __builtin_amdgcn_permlane32_swap(__float_as_uint(ps), __float_as_uint(ps), false, false);
;         ps = __uint_as_float(rr[0]) + __uint_as_float(rr[1]); l_reg = l_reg * alpha + ps; }
;     else if constexpr (k == 17) { PK4(p0, 0, pa0); }
;     else if constexpr (k == 18) { PK4(p0, 8, pa1); }
;     else if constexpr (k == 19) { PK4(p1, 0, pa2); }
;     else if constexpr (k == 20) { PK4(p1, 8, pa3); }
; }
; __device__ __forceinline__ void stage_qk_fin(int kboff, f32x16& x0, f32x16& x1, LAS unsigned char* lds, int r32, int hi, const bf16x8* qr,
;                                              f32x16& y0, f32x16& y1, float alY, float& l_reg, bf16x8& pa0, bf16x8& pa1, bf16x8& pa2, bf16x8& pa3) {
;     x0 = (f32x16){}; x1 = (f32x16){};
;     unsigned kb[4];
; #pragma unroll
;     for (int dd = 0; dd < 4; ++dd) kb[dd] = lds_addr(lds) + K_OFF + kboff + r32 * 384 + (((2 * dd + hi) ^ ((r32 >> 1) & 7)) << 4);
;     ...
;     float ps = 0.f; bf16x8 bA[2], bB[2];
;     SBAR(); KGRP(bA, 0); KGRP(bB, 1); KWAIT(bA, 2); SBAR();
;     KMS(bA, 0); KGRP(bA, 2); KWAIT(bB, 2); SBAR();
;     KMS(bB, 1); KGRP(bB, 3); KWAIT(bA, 2); SBAR();
;     KMS(bA, 2); KGRP(bA, 4); KWAIT(bB, 2); SBAR();
;     KMS(bB, 3); KGRP(bB, 5); KWAIT(bA, 2); SBAR();
;     KMS(bA, 4); KGRP(bA, 6); KWAIT(bB, 2); SBAR();
;     KMS(bB, 5); KGRP(bB, 7); KWAIT(bA, 2); SBAR();
;     KMS(bA, 6); KGRP(bA, 8); KWAIT(bB, 2); SBAR();
;     KMS(bB, 7); KGRP(bB, 9); KWAIT(bA, 2); SBAR();
;     KMS(bA, 8); KGRP(bA, 10); KWAIT(bB, 2); SBAR();
;     KMS(bB, 9); KGRP(bB, 11); KWAIT(bA, 2); SBAR();
;     KMS(bA, 10); KWAIT(bB, 0); SBAR();
;     KMS(bB, 11);
.LBB0_333:
	s_add_i32 s34, s85, 0xffff4000
	s_cmp_lt_i32 s86, s84
	s_cselect_b64 s[86:87], -1, 0
	v_cndmask_b32_e64 v178, v223, 0, s[86:87]
	ds_read_b128 v[2:5], v181 offset:0
	ds_read_b128 v[6:9], v181 offset:0x3000
	ds_read_b128 v[10:13], v219 offset:0
	ds_read_b128 v[112:115], v219 offset:0x3000
	s_nop 0
	s_waitcnt lgkmcnt(2)
	s_nop 0
	v_mfma_f32_32x32x16_bf16 v[96:111], v[2:5], v[128:131], 0
	v_exp_f32_e32 v14, v14
	v_exp_f32_e32 v15, v15
	v_mfma_f32_32x32x16_bf16 v[80:95], v[6:9], v[128:131], 0
	v_exp_f32_e32 v176, v176
	v_exp_f32_e32 v177, v177
	ds_read_b128 v[2:5], v220 offset:0
	ds_read_b128 v[6:9], v220 offset:0x3000
	s_waitcnt lgkmcnt(2)
	s_nop 0
	v_mfma_f32_32x32x16_bf16 v[96:111], v[10:13], v[132:135], v[96:111]
	v_exp_f32_e32 v116, v116
	v_exp_f32_e32 v117, v117
	v_mfma_f32_32x32x16_bf16 v[80:95], v[112:115], v[132:135], v[80:95]
	v_exp_f32_e32 v118, v118
	v_exp_f32_e32 v119, v119
	ds_read_b128 v[10:13], v221 offset:0
	ds_read_b128 v[112:115], v221 offset:0x3000
	s_waitcnt lgkmcnt(2)
	s_nop 0
	v_mfma_f32_32x32x16_bf16 v[96:111], v[2:5], v[136:139], v[96:111]
	v_exp_f32_e32 v120, v120
	v_exp_f32_e32 v121, v121
	v_mfma_f32_32x32x16_bf16 v[80:95], v[6:9], v[136:139], v[80:95]
	v_exp_f32_e32 v122, v122
	v_exp_f32_e32 v123, v123
	ds_read_b128 v[2:5], v181 offset:0x80
	ds_read_b128 v[6:9], v181 offset:0x3080
	s_waitcnt lgkmcnt(2)
	s_nop 0
	v_mfma_f32_32x32x16_bf16 v[96:111], v[10:13], v[140:143], v[96:111]
	v_exp_f32_e32 v124, v124
	v_exp_f32_e32 v125, v125
	v_mfma_f32_32x32x16_bf16 v[80:95], v[112:115], v[140:143], v[80:95]
	v_exp_f32_e32 v126, v126
	v_exp_f32_e32 v127, v127
	ds_read_b128 v[10:13], v219 offset:0x80
	ds_read_b128 v[112:115], v219 offset:0x3080
	s_waitcnt lgkmcnt(2)
	s_nop 0
	v_mfma_f32_32x32x16_bf16 v[96:111], v[2:5], v[144:147], v[96:111]
	v_add_f32_e32 v2, v243, v242
	v_add_f32_e32 v3, v14, v15
	v_add_f32_e32 v2, v2, v3
	v_mfma_f32_32x32x16_bf16 v[80:95], v[6:9], v[144:147], v[80:95]
	v_add_f32_e32 v3, v241, v240
	v_add_f32_e32 v4, v176, v177
	v_add_f32_e32 v3, v3, v4
	v_add_f32_e32 v192, v2, v3
	ds_read_b128 v[2:5], v220 offset:0x80
	ds_read_b128 v[6:9], v220 offset:0x3080
	s_waitcnt lgkmcnt(2)
	s_nop 0
	v_mfma_f32_32x32x16_bf16 v[96:111], v[10:13], v[148:151], v[96:111]
	v_add_f32_e32 v10, v239, v238
	v_add_f32_e32 v11, v116, v117
	v_add_f32_e32 v10, v10, v11
	v_add_f32_e32 v10, v10, v192
	v_mfma_f32_32x32x16_bf16 v[80:95], v[112:115], v[148:151], v[80:95]
	v_add_f32_e32 v11, v237, v236
	v_add_f32_e32 v12, v118, v119
	v_add_f32_e32 v11, v11, v12
	v_add_f32_e32 v192, v11, v10
	ds_read_b128 v[10:13], v221 offset:0x80
	ds_read_b128 v[112:115], v221 offset:0x3080
	s_waitcnt lgkmcnt(2)
	s_nop 0
	v_mfma_f32_32x32x16_bf16 v[96:111], v[2:5], v[152:155], v[96:111]
	v_add_f32_e32 v2, v235, v234
	v_add_f32_e32 v3, v120, v121
	v_add_f32_e32 v2, v2, v3
	v_add_f32_e32 v2, v2, v192
	v_mfma_f32_32x32x16_bf16 v[80:95], v[6:9], v[152:155], v[80:95]
	v_add_f32_e32 v3, v233, v232
	v_add_f32_e32 v4, v122, v123
	v_add_f32_e32 v3, v3, v4
	v_add_f32_e32 v192, v3, v2
	ds_read_b128 v[2:5], v181 offset:0x100
	ds_read_b128 v[6:9], v181 offset:0x3100
	s_waitcnt lgkmcnt(2)
	s_nop 0
	v_mfma_f32_32x32x16_bf16 v[96:111], v[10:13], v[156:159], v[96:111]
	v_add_f32_e32 v10, v231, v230
	v_add_f32_e32 v11, v124, v125
	v_add_f32_e32 v10, v10, v11
	v_add_f32_e32 v10, v10, v192
	v_mfma_f32_32x32x16_bf16 v[80:95], v[112:115], v[156:159], v[80:95]
	v_add_f32_e32 v11, v216, v179
	v_add_f32_e32 v12, v126, v127
	v_add_f32_e32 v11, v11, v12
	v_add_f32_e32 v200, v11, v10
	ds_read_b128 v[10:13], v219 offset:0x100
	ds_read_b128 v[112:115], v219 offset:0x3100
	s_waitcnt lgkmcnt(2)
	s_nop 0
	v_mfma_f32_32x32x16_bf16 v[96:111], v[2:5], v[160:163], v[96:111]
	v_mov_b32_e32 v201, v200
	s_nop 1
	v_permlane32_swap_b32_e32 v200, v201
	v_mfma_f32_32x32x16_bf16 v[80:95], v[6:9], v[160:163], v[80:95]
	v_cvt_pk_bf16_f32 v2, v243, v242
	v_cvt_pk_bf16_f32 v3, v241, v240
	v_cvt_pk_bf16_f32 v4, v239, v238
	v_cvt_pk_bf16_f32 v5, v237, v236
	ds_read_b128 v[194:197], v220 offset:0x100
	ds_read_b128 v[202:205], v220 offset:0x3100
	s_waitcnt lgkmcnt(2)
	s_nop 0
	v_mfma_f32_32x32x16_bf16 v[96:111], v[10:13], v[164:167], v[96:111]
	v_cvt_pk_bf16_f32 v6, v235, v234
	v_cvt_pk_bf16_f32 v7, v233, v232
	v_cvt_pk_bf16_f32 v8, v231, v230
	v_cvt_pk_bf16_f32 v9, v216, v179
	v_mfma_f32_32x32x16_bf16 v[80:95], v[112:115], v[164:167], v[80:95]
	v_cvt_pk_bf16_f32 v10, v14, v15
	v_cvt_pk_bf16_f32 v11, v176, v177
	v_cvt_pk_bf16_f32 v12, v116, v117
	v_cvt_pk_bf16_f32 v13, v118, v119
	ds_read_b128 v[206:209], v221 offset:0x100
	ds_read_b128 v[210:213], v221 offset:0x3100
	s_waitcnt lgkmcnt(2)
	s_nop 0
	v_mfma_f32_32x32x16_bf16 v[96:111], v[194:197], v[168:171], v[96:111]
	v_cvt_pk_bf16_f32 v112, v120, v121
	v_cvt_pk_bf16_f32 v113, v122, v123
	v_cvt_pk_bf16_f32 v114, v124, v125
	v_cvt_pk_bf16_f32 v115, v126, v127
	v_mfma_f32_32x32x16_bf16 v[80:95], v[202:205], v[168:171], v[80:95]
	v_add_f32_e32 v247, v200, v201
	v_fma_f32 v245, v245, v0, v247
	s_waitcnt lgkmcnt(0)
	s_nop 0
	v_mfma_f32_32x32x16_bf16 v[96:111], v[206:209], v[172:175], v[96:111]
	v_mfma_f32_32x32x16_bf16 v[80:95], v[210:213], v[172:175], v[80:95]
	s_cmp_eq_u32 s100, 0
	s_cbranch_scc1 .Lmy_mid_b
	s_waitcnt vmcnt(0)
	s_barrier

; __device__ __forceinline__ void attn_block(const Params& p, LAS unsigned char* lds, int h, int qb) {
;     ...
;     for (int t = 1; t < ntiles; t += 2) {
;         STEP(t, pB0, pB1, mnB, alB, pA0, pA1, alA);
;         if (t + 1 < ntiles) STEP(t + 1, pA0, pA1, mnA, alA, pB0, pB1, alB);
;     }
.LBB0_337:
	s_add_i32 s85, s85, 0x8000
	s_cmp_ge_i32 s82, s80
	s_cbranch_scc1 .LBB0_322
	s_mov_b32 s86, s82
	s_branch .LBB0_326
